# x conversion loop: counted vmcnt(4) at the loop top instead of vmcnt(0) (stores drain in the background); on top of the forget_logits batching
# baseline (speedup 1.0000x reference)
; __device__ __forceinline__ unsigned pk2(float lo, float hi) { return pg8::cvt_pk_bf16(lo, hi); }
; __device__ __forceinline__ void p0_prologue(KArgs A, LAS unsigned char* lds, int G) {
;     ...
;         int m = 2 * gw;
;         if (m < M) {
;             f32x4 v[8]; ldrows(m, v);
;             for (;;) {
;                 const int mn = m + 2 * NGW; const bool hn = mn < M; f32x4 w[8];
; #pragma unroll
;                 for (int i = 0; i < 8; ++i) w[i] = v[i];
;                 if (hn) ldrows(mn, w);
;                 float s0 = 0.f, s1 = 0.f;
; #pragma unroll
;                 for (int j = 0; j < 4; ++j) { s0 += (v[j].x * v[j].x + v[j].y * v[j].y) + (v[j].z * v[j].z + v[j].w * v[j].w); s1 += (v[4 + j].x * v[4 + j].x + v[4 + j].y * v[4 + j].y) + (v[4 + j].z * v[4 + j].z + v[4 + j].w * v[4 + j].w); }
;                 s0 = wave_sum(s0); s1 = wave_sum(s1);
;                 if (lane == 0) { float* sx = (float*)(ws + WS_SSQ) + 3 * M; sx[m] = s0; sx[m + 1] = s1; }
;                 v4u* o16 = (v4u*)((bf16*)(ws + WS_XN) + (size_t)m * D) + lane;
; #pragma unroll
;                 for (int h = 0; h < 4; ++h) { v4u o; o.x = pk2(v[2 * h].x, v[2 * h].y); o.y = pk2(v[2 * h].z, v[2 * h].w); o.z = pk2(v[2 * h + 1].x, v[2 * h + 1].y); o.w = pk2(v[2 * h + 1].z, v[2 * h + 1].w); o16[64 * h] = o; }
;                 if (!hn) break;
;                 m = mn;
; #pragma unroll
;                 for (int i = 0; i < 8; ++i) v[i] = w[i];
.LBB0_580:
	s_add_i32 s10, s0, s4
	s_cmp_lt_i32 s10, 0x8000
	s_cselect_b64 s[14:15], -1, 0
	s_cmpk_gt_i32 s10, 0x7fff
	s_cselect_b64 s[8:9], -1, 0
	s_waitcnt vmcnt(4)
	v_mov_b64_e32 v[64:65], v[28:29]
	v_mov_b64_e32 v[60:61], v[32:33]
	v_mov_b64_e32 v[56:57], v[20:21]
	v_mov_b64_e32 v[52:53], v[24:25]
	v_mov_b64_e32 v[44:45], v[12:13]
	v_mov_b64_e32 v[48:49], v[16:17]
	v_mov_b64_e32 v[36:37], v[4:5]
	v_mov_b64_e32 v[40:41], v[8:9]
	s_and_b64 vcc, exec, s[8:9]
	v_mov_b64_e32 v[62:63], v[26:27]
	v_mov_b64_e32 v[58:59], v[30:31]
	v_mov_b64_e32 v[54:55], v[18:19]
	v_mov_b64_e32 v[50:51], v[22:23]
	v_mov_b64_e32 v[42:43], v[10:11]
	v_mov_b64_e32 v[46:47], v[14:15]
	v_mov_b64_e32 v[34:35], v[2:3]
	v_mov_b64_e32 v[38:39], v[6:7]
	s_cbranch_vccnz .LBB0_582
	s_ashr_i32 s11, s10, 31
	s_lshl_b64 s[20:21], s[10:11], 12
	v_lshl_add_u64 v[58:59], v[66:67], 0, s[20:21]
	s_mov_b64 s[20:21], 0x1000
	global_load_dwordx4 v[34:37], v[58:59], off offset:16
	global_load_dwordx4 v[38:41], v[58:59], off
	global_load_dwordx4 v[42:45], v[58:59], off offset:2064
	global_load_dwordx4 v[46:49], v[58:59], off offset:2048
	v_lshl_add_u64 v[54:55], v[58:59], 0, s[20:21]
	v_add_co_u32_e32 v60, vcc, s7, v58
	s_mov_b64 s[20:21], 0x1800
	s_nop 0
	v_addc_co_u32_e32 v61, vcc, 0, v59, vcc
	v_lshl_add_u64 v[62:63], v[58:59], 0, s[20:21]
	global_load_dwordx4 v[50:53], v[60:61], off
	s_nop 0
	global_load_dwordx4 v[54:57], v[54:55], off offset:16
	s_nop 0
	global_load_dwordx4 v[58:61], v[60:61], off offset:2048
	s_nop 0
	global_load_dwordx4 v[62:65], v[62:63], off offset:16
